# static s_setprio 1 for waves 0-3 only during the GEMM phases (P1 P3 P6 P8 P10), priority 0 elsewhere
# baseline (speedup 1.0000x reference)
; #define LAS __attribute__((address_space(3)))
; __device__ __forceinline__ unsigned xb_add(unsigned* p, unsigned v) { return __hip_atomic_fetch_add(p, v, __ATOMIC_RELAXED, __HIP_MEMORY_SCOPE_AGENT); }
; __device__ __forceinline__ unsigned xb_xcc_id() { return (unsigned)__builtin_amdgcn_s_getreg((3 << 11) | 20) & 0xFu; }
; __device__ __forceinline__ XcdBarrier xcd_barrier_post(unsigned* bar, volatile LAS unsigned* st) {
;     XcdBarrier b; b.bar = bar; b.x = xb_xcc_id(); b.st = st;
;     if (threadIdx.x == 0) (void)xb_add(&bar[XB_XCNT(b.x)], 1u);
;     return b;
; __global__ void __launch_bounds__(512, 2) mk_fwd(Args args) {
;     ...
;     Frame F;
;     F.lds = (LAS unsigned char*)lds_raw; F.tid = threadIdx.x; F.lane = F.tid & 63; F.wave = __builtin_amdgcn_readfirstlane(F.tid >> 6); F.G = gridDim.x;
; #pragma unroll
;     for (int i = 0; i < 30; ++i) F.in[i] = args.in[i];
;     F.out = args.out; F.ws = args.ws;
;     volatile LAS unsigned* MISC = (volatile LAS unsigned*)(F.lds + LDSCTL_OFF);
;     if (F.tid < 64) MISC[F.tid] = 0u;
;     __syncthreads();
;     unsigned* ctl = (unsigned*)(F.ws + WS_CTL);
;     XcdBarrier bar = xcd_barrier_post(ctl + CW_BAR + args.li * XCD_BAR_WORDS, MISC + 8);
_Z6mk_fwd4Args:
	v_readfirstlane_b32 s98, v0
	s_nop 3
	s_and_b32 s98, s98, 0x3ff
	s_lshr_b32 s98, s98, 6
	s_load_dword s96, s[0:1], 0x110
	s_load_dwordx16 s[72:87], s[0:1], 0xc0
	s_mov_b32 s92, s2
	s_add_u32 s2, s0, 0x110
	s_addc_u32 s3, s1, 0
	v_readfirstlane_b32 s94, v0
	v_writelane_b32 v254, s2, 0
	v_cmp_gt_u32_e32 vcc, 64, v0
	s_nop 0
	v_writelane_b32 v254, s3, 1
	s_and_saveexec_b64 s[2:3], vcc
	v_lshl_add_u32 v1, v0, 2, 0
	v_add_u32_e32 v1, 0x27f00, v1
	v_mov_b32_e32 v2, 0
	ds_write_b32 v1, v2
	s_or_b64 exec, exec, s[2:3]
	s_load_dwordx16 s[4:19], s[0:1], 0x0
	s_waitcnt lgkmcnt(0)
	v_writelane_b32 v254, s4, 2
	s_nop 1
	v_writelane_b32 v254, s5, 3
	v_writelane_b32 v254, s6, 4
	v_writelane_b32 v254, s7, 5
	v_writelane_b32 v254, s8, 6
	v_writelane_b32 v254, s9, 7
	v_writelane_b32 v254, s10, 8
	v_writelane_b32 v254, s11, 9
	v_writelane_b32 v254, s12, 10
	v_writelane_b32 v254, s13, 11
	v_writelane_b32 v254, s14, 12
	v_writelane_b32 v254, s15, 13
	v_writelane_b32 v254, s16, 14
	v_writelane_b32 v254, s17, 15
	v_writelane_b32 v254, s18, 16
	v_writelane_b32 v254, s19, 17
	s_load_dword s2, s[0:1], 0x108
	s_load_dwordx16 s[4:19], s[0:1], 0x80
	s_waitcnt lgkmcnt(0)
	s_barrier
	s_mulk_i32 s2, 0xd80
	v_writelane_b32 v254, s4, 18
	s_ashr_i32 s3, s2, 31
	s_lshl_b64 s[2:3], s[2:3], 2
	v_writelane_b32 v254, s5, 19
	v_writelane_b32 v254, s6, 20
	v_writelane_b32 v254, s7, 21
	v_writelane_b32 v254, s8, 22
	v_writelane_b32 v254, s9, 23
	v_writelane_b32 v254, s10, 24
	v_writelane_b32 v254, s11, 25
	v_writelane_b32 v254, s12, 26
	v_writelane_b32 v254, s13, 27
	v_writelane_b32 v254, s14, 28
	v_writelane_b32 v254, s15, 29
	v_writelane_b32 v254, s16, 30
	s_add_u32 s2, s86, s2
	v_writelane_b32 v254, s17, 31
	s_addc_u32 s3, s87, s3
	v_writelane_b32 v254, s18, 32
	s_add_u32 s2, s2, 0x1000
	v_writelane_b32 v254, s19, 33
	s_addc_u32 s3, s3, 0
	v_writelane_b32 v254, s2, 34
	v_cmp_eq_u32_e64 s[4:5], 0, v0
	s_nop 0
	v_writelane_b32 v254, s3, 35
	s_getreg_b32 s2, hwreg(HW_REG_XCC_ID, 0, 4)
	s_and_b32 s2, s2, 15
	v_writelane_b32 v254, s2, 36
	s_mov_b64 s[2:3], exec
	v_writelane_b32 v254, s4, 37
	s_nop 1
	v_writelane_b32 v254, s5, 38
	s_and_b64 s[4:5], s[2:3], s[4:5]
	s_mov_b64 exec, s[4:5]
	s_cbranch_execz .LBB0_5
	s_mov_b64 s[4:5], exec
	v_mbcnt_lo_u32_b32 v1, s4, 0
	v_mbcnt_hi_u32_b32 v1, s5, v1
	v_cmp_eq_u32_e32 vcc, 0, v1
	s_and_b64 s[6:7], exec, vcc
	s_mov_b64 exec, s[6:7]
	s_cbranch_execz .LBB0_5
	v_readlane_b32 s6, v254, 36
	s_bcnt1_i32_b64 s4, s[4:5]
	s_lshl_b32 s6, s6, 8
	v_mov_b32_e32 v2, s4
	v_readlane_b32 s4, v254, 34
	v_mov_b32_e32 v1, s6
	v_readlane_b32 s5, v254, 35
	s_nop 4
	global_atomic_add v1, v2, s[4:5] offset:1024

; #define LAS __attribute__((address_space(3)))
; #define SEAM(k) do { if (IN(k) && IN((k) + 1)) xcd_barrier(bar); } while (0)
; __global__ void __launch_bounds__(512, 2) mk_fwd(Args args) {
;     ...
;     if (IN(1)) {
;         const bool roles = (F.G == 256);
;         const int x = (int)blockIdx.x & 7, j = (int)blockIdx.x >> 3; const bool is_gemm = !roles || j < G1_PER + (x < G1_HI ? 1 : 0);
;         if (!is_gemm) { const int sidx = (j == G1_PER) ? x - G1_HI : (8 - G1_HI) + (j - G1_PER - 1) * 8 + x; p0_late_weights(F, sidx * 8 + F.wave, NSTREAM * 8); }
;         else { pg8::Gemm g{WSP(bf16_t, WS_XB), WSP(bf16_t, WS_BT1), M, N1P, DM, DM, DM}; pg8::StaticOrder S0; S0.init(M, N1P, roles ? NGEMM1 : F.G, (int)blockIdx.x);
;             pg8::ChunkOrder S{S0, roles ? G1_PER : ((F.G & 7) == 0 ? F.G >> 3 : 0), roles ? G1_HI : 0};
;             EpiProjConv E{F.ws, F.out, F.in[9], F.in[10], F.in[17], F.in[18], F.in[19], F.in[3], F.in[5], (LAS float*)(F.lds + RING_BYTES)};
;             pg8::gemm_phase<EpiProjConv, pg8::GeomPlain, pg8::ChunkOrder, true>(F.lds, g, S, E); } } SEAM(1);
.LBB0_148:
	s_cmp_lt_u32 s98, 4
	s_cbranch_scc0 .Lprio_x1
	s_setprio 1

; __device__ __forceinline__ unsigned xb_ld(unsigned* p)              { return __hip_atomic_load(p, __ATOMIC_RELAXED, __HIP_MEMORY_SCOPE_AGENT); }
; __device__ __forceinline__ void xcd_barrier_complete(unsigned* bar, unsigned x, unsigned& nloc, unsigned& nx) {
;     const unsigned G = gridDim.x * gridDim.y * gridDim.z;
;     unsigned sum, cnt, mine, sp = 0u;
;     for (;;) {
;         sum = 0u; cnt = 0u; mine = 0u;
; #pragma unroll
;         for (unsigned j = 0; j < 16; ++j) { const unsigned c = xb_ld(&bar[XB_XCNT(j)]); sum += c; cnt += (c > 0u) ? 1u : 0u; mine = (j == x) ? c : mine; }
;         if (sum == G) break;
; __device__ __forceinline__ void xcd_barrier(const XcdBarrier& b) {
;     asm volatile("s_waitcnt vmcnt(0)" ::: "memory");
;     __syncthreads();
;     if (threadIdx.x == 0) {
;         unsigned* bar = b.bar;
;         __builtin_amdgcn_s_waitcnt(0);
;         unsigned nloc = b.st[0], nx = b.st[1];
;         if (nloc == 0u) { xcd_barrier_complete(bar, b.x, nloc, nx); b.st[0] = nloc; b.st[1] = nx; }
.LBB0_1796:
	s_cmp_gt_u32 s91, 2
	s_cselect_b64 s[0:1], -1, 0
	s_and_b64 s[0:1], s[28:29], s[0:1]
	s_andn2_b64 vcc, exec, s[0:1]
	s_cbranch_vccnz .LBB0_1850
	s_setprio 0
	s_waitcnt vmcnt(0)
	s_waitcnt lgkmcnt(0)
	s_barrier
	s_mov_b64 s[0:1], exec
	v_readlane_b32 s2, v254, 37
	v_readlane_b32 s3, v254, 38
	s_and_b64 s[2:3], s[0:1], s[2:3]
	s_mov_b64 exec, s[2:3]
	s_cbranch_execz .LBB0_1849
	s_add_i32 s2, 0, 0x27f20
	v_mov_b32_e32 v1, s2
	s_waitcnt vmcnt(0) expcnt(0) lgkmcnt(0)
	ds_read_b32 v3, v1
	s_add_i32 s2, 0, 0x27f24
	v_mov_b32_e32 v1, s2
	ds_read_b32 v1, v1
	s_waitcnt lgkmcnt(1)
	v_cmp_ne_u32_e32 vcc, 0, v3
	s_cbranch_vccnz .LBB0_1813
	v_readlane_b32 s2, v254, 0
	v_readlane_b32 s3, v254, 1
	s_load_dwordx2 s[6:7], s[2:3], 0x4
	v_readlane_b32 s8, v254, 34
	v_readlane_b32 s9, v254, 35
	s_add_u32 s2, s8, 0x1000
	s_addc_u32 s3, s9, 0
	s_add_u32 s4, s8, 0x1100
	s_addc_u32 s5, s9, 0
	s_waitcnt lgkmcnt(0)
	s_mul_i32 s16, s6, s96
	s_add_u32 s6, s8, 0x1200
	s_mul_i32 s16, s16, s7
	s_addc_u32 s7, s9, 0
	s_add_u32 s8, s8, 0x1300
	s_addc_u32 s9, s9, 0
	s_mov_b32 s17, 1
	v_mov_b32_e32 v17, 0
	s_branch .LBB0_1801

; __device__ __forceinline__ unsigned xb_ld(unsigned* p)              { return __hip_atomic_load(p, __ATOMIC_RELAXED, __HIP_MEMORY_SCOPE_AGENT); }
; __device__ __forceinline__ void xcd_barrier_complete(unsigned* bar, unsigned x, unsigned& nloc, unsigned& nx) {
;     const unsigned G = gridDim.x * gridDim.y * gridDim.z;
;     unsigned sum, cnt, mine, sp = 0u;
;     for (;;) {
;         sum = 0u; cnt = 0u; mine = 0u;
; #pragma unroll
;         for (unsigned j = 0; j < 16; ++j) { const unsigned c = xb_ld(&bar[XB_XCNT(j)]); sum += c; cnt += (c > 0u) ? 1u : 0u; mine = (j == x) ? c : mine; }
;         if (sum == G) break;
; __device__ __forceinline__ void xcd_barrier(const XcdBarrier& b) {
;     asm volatile("s_waitcnt vmcnt(0)" ::: "memory");
;     __syncthreads();
;     if (threadIdx.x == 0) {
;         unsigned* bar = b.bar;
;         __builtin_amdgcn_s_waitcnt(0);
;         unsigned nloc = b.st[0], nx = b.st[1];
;         if (nloc == 0u) { xcd_barrier_complete(bar, b.x, nloc, nx); b.st[0] = nloc; b.st[1] = nx; }
.LBB0_1950:
	s_cmp_gt_i32 s91, 4
	s_cselect_b64 s[0:1], -1, 0
	s_and_b64 s[2:3], s[2:3], s[0:1]
	s_andn2_b64 vcc, exec, s[2:3]
	s_cbranch_vccnz .LBB0_2004
	s_setprio 0
	s_waitcnt vmcnt(0)
	s_waitcnt lgkmcnt(0)
	s_barrier
	s_mov_b64 s[2:3], exec
	v_readlane_b32 s4, v254, 37
	v_readlane_b32 s5, v254, 38
	s_and_b64 s[4:5], s[2:3], s[4:5]
	s_mov_b64 exec, s[4:5]
	s_cbranch_execz .LBB0_2003
	s_add_i32 s4, 0, 0x27f20
	v_mov_b32_e32 v1, s4
	s_waitcnt vmcnt(0) expcnt(0) lgkmcnt(0)
	ds_read_b32 v3, v1
	s_add_i32 s4, 0, 0x27f24
	v_mov_b32_e32 v1, s4
	ds_read_b32 v1, v1
	s_waitcnt lgkmcnt(1)
	v_cmp_ne_u32_e32 vcc, 0, v3
	s_cbranch_vccnz .LBB0_1967
	v_readlane_b32 s4, v254, 0
	v_readlane_b32 s5, v254, 1
	s_load_dwordx2 s[8:9], s[4:5], 0x4
	v_readlane_b32 s10, v254, 34
	v_readlane_b32 s11, v254, 35
	s_add_u32 s4, s10, 0x1000
	s_addc_u32 s5, s11, 0
	s_add_u32 s6, s10, 0x1100
	s_addc_u32 s7, s11, 0
	s_waitcnt lgkmcnt(0)
	s_mul_i32 s18, s8, s96
	s_add_u32 s8, s10, 0x1200
	s_mul_i32 s18, s18, s9
	s_addc_u32 s9, s11, 0
	s_add_u32 s10, s10, 0x1300
	s_addc_u32 s11, s11, 0
	s_mov_b32 s19, 1
	v_mov_b32_e32 v17, 0
	s_branch .LBB0_1955

; __device__ __forceinline__ unsigned xb_ld(unsigned* p)              { return __hip_atomic_load(p, __ATOMIC_RELAXED, __HIP_MEMORY_SCOPE_AGENT); }
; __device__ __forceinline__ void xcd_barrier_complete(unsigned* bar, unsigned x, unsigned& nloc, unsigned& nx) {
;     const unsigned G = gridDim.x * gridDim.y * gridDim.z;
;     unsigned sum, cnt, mine, sp = 0u;
;     for (;;) {
;         sum = 0u; cnt = 0u; mine = 0u;
; #pragma unroll
;         for (unsigned j = 0; j < 16; ++j) { const unsigned c = xb_ld(&bar[XB_XCNT(j)]); sum += c; cnt += (c > 0u) ? 1u : 0u; mine = (j == x) ? c : mine; }
;         if (sum == G) break;
; __device__ __forceinline__ void xcd_barrier(const XcdBarrier& b) {
;     asm volatile("s_waitcnt vmcnt(0)" ::: "memory");
;     __syncthreads();
;     if (threadIdx.x == 0) {
;         unsigned* bar = b.bar;
;         __builtin_amdgcn_s_waitcnt(0);
;         unsigned nloc = b.st[0], nx = b.st[1];
;         if (nloc == 0u) { xcd_barrier_complete(bar, b.x, nloc, nx); b.st[0] = nloc; b.st[1] = nx; }
.LBB0_2247:
	s_cmp_gt_i32 s91, 7
	s_cselect_b64 s[2:3], -1, 0
	s_and_b64 s[0:1], s[0:1], s[2:3]
	s_andn2_b64 vcc, exec, s[0:1]
	s_cbranch_vccnz .LBB0_2301
	s_setprio 0
	s_waitcnt vmcnt(0)
	s_waitcnt lgkmcnt(0)
	s_barrier
	s_mov_b64 s[0:1], exec
	v_readlane_b32 s4, v254, 37
	v_readlane_b32 s5, v254, 38
	s_and_b64 s[4:5], s[0:1], s[4:5]
	s_mov_b64 exec, s[4:5]
	s_cbranch_execz .LBB0_2300
	s_add_i32 s4, 0, 0x27f20
	v_mov_b32_e32 v1, s4
	s_waitcnt vmcnt(0) expcnt(0) lgkmcnt(0)
	ds_read_b32 v3, v1
	s_add_i32 s4, 0, 0x27f24
	v_mov_b32_e32 v1, s4
	ds_read_b32 v1, v1
	s_waitcnt lgkmcnt(1)
	v_cmp_ne_u32_e32 vcc, 0, v3
	s_cbranch_vccnz .LBB0_2264
	v_readlane_b32 s4, v254, 0
	v_readlane_b32 s5, v254, 1
	s_load_dwordx2 s[8:9], s[4:5], 0x4
	v_readlane_b32 s10, v254, 34
	v_readlane_b32 s11, v254, 35
	s_add_u32 s4, s10, 0x1000
	s_addc_u32 s5, s11, 0
	s_add_u32 s6, s10, 0x1100
	s_addc_u32 s7, s11, 0
	s_waitcnt lgkmcnt(0)
	s_mul_i32 s18, s8, s96
	s_add_u32 s8, s10, 0x1200
	s_mul_i32 s18, s18, s9
	s_addc_u32 s9, s11, 0
	s_add_u32 s10, s10, 0x1300
	s_addc_u32 s11, s11, 0
	s_mov_b32 s19, 1
	v_mov_b32_e32 v17, 0
	s_branch .LBB0_2252

; __device__ __forceinline__ unsigned xb_ld(unsigned* p)              { return __hip_atomic_load(p, __ATOMIC_RELAXED, __HIP_MEMORY_SCOPE_AGENT); }
; __device__ __forceinline__ void xcd_barrier_complete(unsigned* bar, unsigned x, unsigned& nloc, unsigned& nx) {
;     const unsigned G = gridDim.x * gridDim.y * gridDim.z;
;     unsigned sum, cnt, mine, sp = 0u;
;     for (;;) {
;         sum = 0u; cnt = 0u; mine = 0u;
; #pragma unroll
;         for (unsigned j = 0; j < 16; ++j) { const unsigned c = xb_ld(&bar[XB_XCNT(j)]); sum += c; cnt += (c > 0u) ? 1u : 0u; mine = (j == x) ? c : mine; }
;         if (sum == G) break;
; __device__ __forceinline__ void xcd_barrier(const XcdBarrier& b) {
;     asm volatile("s_waitcnt vmcnt(0)" ::: "memory");
;     __syncthreads();
;     if (threadIdx.x == 0) {
;         unsigned* bar = b.bar;
;         __builtin_amdgcn_s_waitcnt(0);
;         unsigned nloc = b.st[0], nx = b.st[1];
;         if (nloc == 0u) { xcd_barrier_complete(bar, b.x, nloc, nx); b.st[0] = nloc; b.st[1] = nx; }
.LBB0_2744:
	s_cmp_gt_i32 s91, 9
	s_cselect_b64 s[2:3], -1, 0
	s_and_b64 s[0:1], s[20:21], s[2:3]
	s_andn2_b64 vcc, exec, s[0:1]
	v_readlane_b32 s66, v254, 40
	s_cbranch_vccnz .LBB0_2798
	s_setprio 0
	s_waitcnt vmcnt(0)
	s_waitcnt lgkmcnt(0)
	s_barrier
	s_mov_b64 s[0:1], exec
	v_readlane_b32 s4, v254, 37
	v_readlane_b32 s5, v254, 38
	s_and_b64 s[4:5], s[0:1], s[4:5]
	s_mov_b64 exec, s[4:5]
	s_cbranch_execz .LBB0_2797
	s_add_i32 s4, 0, 0x27f20
	v_mov_b32_e32 v1, s4
	s_waitcnt vmcnt(0) expcnt(0) lgkmcnt(0)
	ds_read_b32 v3, v1
	s_add_i32 s4, 0, 0x27f24
	v_mov_b32_e32 v1, s4
	ds_read_b32 v1, v1
	s_waitcnt lgkmcnt(1)
	v_cmp_ne_u32_e32 vcc, 0, v3
	s_cbranch_vccnz .LBB0_2761
	v_readlane_b32 s4, v254, 0
	v_readlane_b32 s5, v254, 1
	s_load_dwordx2 s[8:9], s[4:5], 0x4
	v_readlane_b32 s10, v254, 34
	v_readlane_b32 s11, v254, 35
	s_add_u32 s4, s10, 0x1000
	s_addc_u32 s5, s11, 0
	s_add_u32 s6, s10, 0x1100
	s_addc_u32 s7, s11, 0
	s_waitcnt lgkmcnt(0)
	s_mul_i32 s18, s8, s96
	s_add_u32 s8, s10, 0x1200
	s_mul_i32 s18, s18, s9
	s_addc_u32 s9, s11, 0
	s_add_u32 s10, s10, 0x1300
	s_addc_u32 s11, s11, 0
	s_mov_b32 s19, 1
	v_mov_b32_e32 v17, 0
	s_branch .LBB0_2749

; __device__ __forceinline__ unsigned xb_ld(unsigned* p)              { return __hip_atomic_load(p, __ATOMIC_RELAXED, __HIP_MEMORY_SCOPE_AGENT); }
; __device__ __forceinline__ void xcd_barrier_complete(unsigned* bar, unsigned x, unsigned& nloc, unsigned& nx) {
;     const unsigned G = gridDim.x * gridDim.y * gridDim.z;
;     unsigned sum, cnt, mine, sp = 0u;
;     for (;;) {
;         sum = 0u; cnt = 0u; mine = 0u;
; #pragma unroll
;         for (unsigned j = 0; j < 16; ++j) { const unsigned c = xb_ld(&bar[XB_XCNT(j)]); sum += c; cnt += (c > 0u) ? 1u : 0u; mine = (j == x) ? c : mine; }
;         if (sum == G) break;
; __device__ __forceinline__ void xcd_barrier(const XcdBarrier& b) {
;     asm volatile("s_waitcnt vmcnt(0)" ::: "memory");
;     __syncthreads();
;     if (threadIdx.x == 0) {
;         unsigned* bar = b.bar;
;         __builtin_amdgcn_s_waitcnt(0);
;         unsigned nloc = b.st[0], nx = b.st[1];
;         if (nloc == 0u) { xcd_barrier_complete(bar, b.x, nloc, nx); b.st[0] = nloc; b.st[1] = nx; }
.LBB0_2888:
	s_cmp_gt_i32 s91, 11
	s_cselect_b64 s[0:1], -1, 0
	s_and_b64 s[2:3], s[6:7], s[0:1]
	s_andn2_b64 vcc, exec, s[2:3]
	s_cbranch_vccnz .LBB0_2942
	s_setprio 0
	s_waitcnt vmcnt(0)
	s_waitcnt lgkmcnt(0)
	s_barrier
	s_mov_b64 s[2:3], exec
	v_readlane_b32 s4, v254, 37
	v_readlane_b32 s5, v254, 38
	s_and_b64 s[4:5], s[2:3], s[4:5]
	s_mov_b64 exec, s[4:5]
	s_cbranch_execz .LBB0_2941
	s_add_i32 s4, 0, 0x27f20
	v_mov_b32_e32 v1, s4
	s_waitcnt vmcnt(0) expcnt(0) lgkmcnt(0)
	ds_read_b32 v3, v1
	s_add_i32 s4, 0, 0x27f24
	v_mov_b32_e32 v1, s4
	ds_read_b32 v1, v1
	s_waitcnt lgkmcnt(1)
	v_cmp_ne_u32_e32 vcc, 0, v3
	s_cbranch_vccnz .LBB0_2905
	v_readlane_b32 s4, v254, 0
	v_readlane_b32 s5, v254, 1
	s_load_dwordx2 s[8:9], s[4:5], 0x4
	v_readlane_b32 s10, v254, 34
	v_readlane_b32 s11, v254, 35
	s_add_u32 s4, s10, 0x1000
	s_addc_u32 s5, s11, 0
	s_add_u32 s6, s10, 0x1100
	s_addc_u32 s7, s11, 0
	s_waitcnt lgkmcnt(0)
	s_mul_i32 s18, s8, s96
	s_add_u32 s8, s10, 0x1200
	s_mul_i32 s18, s18, s9
	s_addc_u32 s9, s11, 0
	s_add_u32 s10, s10, 0x1300
	s_addc_u32 s11, s11, 0
	s_mov_b32 s19, 1
	v_mov_b32_e32 v17, 0
	s_branch .LBB0_2893
